# MLA loop: all LDS-DMA issue moved to waves 4-7 (one whole tile per wave, pieces via the instruction offset), static priority now on the compute-only waves 0-3
# speedup vs baseline: 1.0975x; 1.0083x over previous
; DEVINL i32x8 mk6(int a, int b, int c, int d, int e, int f) { i32x8 r = __builtin_nondeterministic_value(r); r[0] = a; r[1] = b; r[2] = c; r[3] = d; r[4] = e; r[5] = f; return r; }
; #define MFMA6(A, B, C) __builtin_amdgcn_mfma_scale_f32_32x32x64_f8f6f4(A, B, C, 2, 2, 0, 0x7f7f7f7f, 0, 0x7f7f7f7f)
; #define ISSUE_K(j) do { const int _t = (j) < NT ? (j) : NT - 1; char* _d = K_lds + ((j) & 3) * SHM_K8; if (wid < 6) GLDS(K8 + (size_t)_t * 6144 + t16u, _d + tid16); \
;     if (wid < 3) GLDS(Kp8 + (size_t)_t * 3072 + t16u, _d + 6144 + tid16); } while (0)
; #define ISSUE_V(j) do { const int _t = (j) < NT ? (j) : NT - 1; GLDS(V8 + (size_t)_t * 8192 + t16u, V_lds + ((j) & 3) * SHM_V8 + tid16); } while (0)
; #define TILE_SYNC() do { asm volatile("s_waitcnt vmcnt(0)" ::: "memory"); __syncthreads(); } while (0)
; template <bool FUSE>
; DEVINL void qkt(f32x16& p0, f32x16& p1, const char* Ks, const i32x8* q8, int r32, int hi, f32x16& e1) {
;   p0 = f32x16{}; p1 = f32x16{};
;   const char* ka = Ks + hi * 1024 + r32 * 16; const char* kb = Ks + 4096 + hi * 512 + r32 * 8;
;   const char* ra = Ks + 6144 + hi * 1024 + r32 * 16; const char* rb = Ks + 6144 + 2048 + hi * 512 + r32 * 8;
;   u32x4 fa[3][2]; u32x2 fb[3][2];
;     ...
;   QK_LD(0, 0);
; #pragma unroll
;   for (int t = 0; t < 3; ++t) {
;     if (t + 1 < 3) QK_LD(t + 1, (t + 1) % 3);
;     const i32x8 a0 = mk6((int)fa[t][0][0], (int)fa[t][0][1], (int)fa[t][0][2], (int)fa[t][0][3], (int)fb[t][0][0], (int)fb[t][0][1]);
;     const i32x8 a1 = mk6((int)fa[t][1][0], (int)fa[t][1][1], (int)fa[t][1][2], (int)fa[t][1][3], (int)fb[t][1][0], (int)fb[t][1][1]);
;     p0 = MFMA6(a0, q8[t], p0);
; DEVINL void mla_block(const Params& p, const bf16_t* __restrict__ Qn, const bf16_t* __restrict__ Qr, const char* __restrict__ K8, const char* __restrict__ Kp8,
;                       const char* __restrict__ V8, const bf16_t* __restrict__ Gb, bf16_t* __restrict__ Yb, char* lds, int pos0) {
;     ...
;   ISSUE_K(0); ISSUE_K(1); ISSUE_K(2); ISSUE_V(0); ISSUE_V(1); TILE_SYNC();
;   qkt<false>(pA0, pA1, KS(0), q8, r32, hi, pA1); partialSM(pA0, pA1, m_reg, mnA, alA, 64, hi);
.LBB0_559:
	s_or_b64 exec, exec, s[8:9]
	s_mul_i32 s8, s75, 0x208000
	s_add_u32 s14, s58, s8
	v_add_u32_e32 v0, 0x9000, v172
	s_addc_u32 s15, s59, 0
	v_readfirstlane_b32 s9, v0
	v_add_u32_e32 v2, 0xb000, v172
	v_lshl_add_u64 v[140:141], s[14:15], 0, v[138:139]
	s_mov_b32 m0, s9
	v_readfirstlane_b32 s9, v2
	global_load_lds_dwordx4 v[140:141], off
	v_lshl_add_u64 v[0:1], v[140:141], 0, s[48:49]
	s_mov_b32 m0, s9
	v_lshlrev_b32_e32 v170, 9, v48
	global_load_lds_dwordx4 v[0:1], off
	v_and_b32_e32 v0, 0x3fffffc0, v166
	v_lshl_add_u32 v171, v0, 2, s68
	v_add_u32_e32 v0, 0, v170
	v_lshlrev_b32_e32 v176, 3, v167
	v_lshlrev_b32_e32 v175, 4, v167
	v_add_u32_e32 v49, v0, v176
	v_add3_u32 v173, v0, v170, v175
	v_add_u32_e32 v0, 0x1000, v49
	s_waitcnt vmcnt(0)
	s_waitcnt vmcnt(0) lgkmcnt(0)
	s_barrier
	ds_read2_b64 v[4:7], v0 offset1:32
	ds_read_b128 v[50:53], v173 offset:2048
	ds_read_b128 v[56:59], v173 offset:2560
	ds_read2_b64 v[60:63], v0 offset0:128 offset1:160
	ds_read_b128 v[16:19], v173 offset:512
	ds_read_b128 v[0:3], v173
	s_waitcnt lgkmcnt(5)
	v_mov_b32_e32 v20, v6
	v_mov_b32_e32 v21, v7
	s_waitcnt lgkmcnt(0)
	v_mfma_scale_f32_32x32x64_f8f6f4 v[32:47], v[0:5], v[120:125], 0, v162, v162 op_sel_hi:[0,0,0] cbsz:2 blgp:2
	s_mov_b32 s12, s13
	s_mov_b32 s14, s13
	s_mov_b32 s15, s13
	s_mov_b32 s16, s13
	s_mov_b32 s17, s13
	s_mov_b32 s18, s13
	s_mov_b32 s19, s13
	v_mfma_scale_f32_32x32x64_f8f6f4 v[16:31], v[16:21], v[120:125], 0, v162, v162 op_sel_hi:[0,0,0] cbsz:2 blgp:2
	s_mov_b32 s20, s13
	s_mov_b32 s21, s13
	s_mov_b32 s22, s13
	s_mov_b32 s23, s13
	s_mov_b32 s24, s13
	s_mov_b32 s25, s13
	s_mov_b32 s26, s13
	s_mov_b32 s27, s13
	v_mov_b64_e32 v[0:1], s[12:13]
	v_and_b32_e32 v169, 63, v166
	v_lshlrev_b32_e32 v174, 10, v48
	s_mov_b32 s53, 4
	v_mov_b64_e32 v[2:3], s[14:15]
	v_mov_b64_e32 v[4:5], s[16:17]
	v_mov_b64_e32 v[6:7], s[18:19]
	v_mov_b64_e32 v[8:9], s[20:21]
	v_mov_b64_e32 v[10:11], s[22:23]
	v_mov_b64_e32 v[12:13], s[24:25]
	v_mov_b64_e32 v[14:15], s[26:27]
	v_mov_b32_e32 v54, v60
	v_mov_b32_e32 v55, v61
	v_mov_b32_e32 v60, v62
	v_mov_b32_e32 v61, v63
	v_add_u32_e32 v49, 0x2000, v49
	v_mfma_scale_f32_32x32x64_f8f6f4 v[32:47], v[50:55], v[126:131], v[32:47], v162, v162 op_sel_hi:[0,0,0] cbsz:2 blgp:2
	ds_read_b128 v[50:53], v173 offset:6144
	ds_read_b128 v[62:65], v173 offset:6656
	ds_read2_b64 v[66:69], v49 offset1:32
	v_mfma_scale_f32_32x32x64_f8f6f4 v[16:31], v[56:61], v[126:131], v[16:31], v162, v162 op_sel_hi:[0,0,0] cbsz:2 blgp:2
	s_waitcnt lgkmcnt(0)
; #define SBAR() __builtin_amdgcn_sched_barrier(0)
; #define ISSUE_K(j) do { const int _t = (j) < NT ? (j) : NT - 1; char* _d = K_lds + ((j) & 3) * SHM_K8; if (wid < 6) GLDS(K8 + (size_t)_t * 6144 + t16u, _d + tid16); \
;     if (wid < 3) GLDS(Kp8 + (size_t)_t * 3072 + t16u, _d + 6144 + tid16); } while (0)
; #define ISSUE_V(j) do { const int _t = (j) < NT ? (j) : NT - 1; GLDS(V8 + (size_t)_t * 8192 + t16u, V_lds + ((j) & 3) * SHM_V8 + tid16); } while (0)
; DEVINL void mla_block(const Params& p, const bf16_t* __restrict__ Qn, const bf16_t* __restrict__ Qr, const char* __restrict__ K8, const char* __restrict__ Kp8,
;                       const char* __restrict__ V8, const bf16_t* __restrict__ Gb, bf16_t* __restrict__ Yb, char* lds, int pos0) {
;     ...
;     ISSUE_K(j + 2); ISSUE_K(j + 3); ISSUE_V(j + 1); ISSUE_V(j + 2); SBAR();
	v_mov_b32_e32 v54, v66
	v_mov_b32_e32 v55, v67
	v_mov_b32_e32 v66, v68
	v_mov_b32_e32 v67, v69
	v_mfma_scale_f32_32x32x64_f8f6f4 v[32:47], v[50:55], v[132:137], v[32:47], v162, v162 op_sel_hi:[0,0,0] cbsz:2 blgp:2
	s_nop 0
	v_mfma_scale_f32_32x32x64_f8f6f4 v[16:31], v[62:67], v[132:137], v[16:31], v162, v162 op_sel_hi:[0,0,0] cbsz:2 blgp:2
	s_nop 9
	v_max_f32_e32 v49, v33, v33
	v_max_f32_e32 v50, v32, v32
	v_max_f32_e32 v49, v50, v49
	v_max3_f32 v49, v49, v34, v35
	v_max3_f32 v49, v49, v36, v37
	v_max3_f32 v49, v49, v38, v39
	v_max3_f32 v49, v49, v40, v41
	v_max3_f32 v49, v49, v42, v43
	v_max3_f32 v49, v49, v44, v45
	v_max3_f32 v49, v49, v46, v47
	v_max3_f32 v49, v49, v16, v17
	v_max3_f32 v49, v49, v18, v19
	v_max3_f32 v49, v49, v20, v21
	v_max3_f32 v49, v49, v22, v23
	v_max3_f32 v49, v49, v24, v25
	v_max3_f32 v49, v49, v26, v27
	v_max3_f32 v49, v49, v28, v29
	v_max3_f32 v49, v49, v30, v31
	v_mov_b32_e32 v50, v49
	s_nop 1
	v_permlane32_swap_b32_e32 v49, v50
	v_max_f32_e32 v50, v50, v50
	v_max_f32_e32 v49, v49, v49
	v_max_f32_e32 v49, v49, v50
	v_add_f32_e32 v50, 0x7149f2ca, v49
	v_max_f32_e32 v49, 0xf149f2ca, v49
	v_sub_f32_e32 v51, 0xf149f2ca, v49
	v_mul_f32_e32 v51, 0x3dd53b94, v51
	v_cmp_ge_f32_e32 vcc, s69, v50
	v_exp_f32_e32 v51, v51
	s_cmp_eq_u64 vcc, exec
	s_cselect_b64 vcc, -1, 0
	v_cndmask_b32_e32 v181, v49, v163, vcc
	v_fmamk_f32 v50, v181, 0xbdd53b94, v164
	v_pk_fma_f32 v[32:33], v[32:33], s[50:51], v[50:51] op_sel_hi:[1,0,0]
	v_pk_fma_f32 v[34:35], v[34:35], s[50:51], v[50:51] op_sel_hi:[1,0,0]
	v_pk_fma_f32 v[36:37], v[36:37], s[50:51], v[50:51] op_sel_hi:[1,0,0]
	v_pk_fma_f32 v[38:39], v[38:39], s[50:51], v[50:51] op_sel_hi:[1,0,0]
	v_pk_fma_f32 v[40:41], v[40:41], s[50:51], v[50:51] op_sel_hi:[1,0,0]
	v_pk_fma_f32 v[42:43], v[42:43], s[50:51], v[50:51] op_sel_hi:[1,0,0]
	v_pk_fma_f32 v[44:45], v[44:45], s[50:51], v[50:51] op_sel_hi:[1,0,0]
	v_pk_fma_f32 v[46:47], v[46:47], s[50:51], v[50:51] op_sel_hi:[1,0,0]
	v_exp_f32_e32 v65, v32
	v_exp_f32_e32 v197, v33
	v_exp_f32_e32 v187, v34
	v_exp_f32_e32 v189, v35
	v_exp_f32_e32 v195, v36
	v_exp_f32_e32 v196, v37
	v_exp_f32_e32 v191, v38
	v_exp_f32_e32 v192, v39
	v_exp_f32_e32 v193, v40
	v_exp_f32_e32 v194, v41
	v_exp_f32_e32 v183, v42
	v_exp_f32_e32 v184, v43
	v_exp_f32_e32 v188, v44
	v_exp_f32_e32 v190, v45
	v_exp_f32_e32 v185, v46
	v_exp_f32_e32 v186, v47
	s_add_u32 s8, s30, s8
	v_cndmask_b32_e64 v179, v51, 1.0, vcc
	v_pk_fma_f32 v[148:149], v[30:31], s[50:51], v[50:51] op_sel_hi:[1,0,0]
	v_pk_fma_f32 v[150:151], v[28:29], s[50:51], v[50:51] op_sel_hi:[1,0,0]
	v_pk_fma_f32 v[152:153], v[26:27], s[50:51], v[50:51] op_sel_hi:[1,0,0]
	v_pk_fma_f32 v[154:155], v[24:25], s[50:51], v[50:51] op_sel_hi:[1,0,0]
	v_pk_fma_f32 v[156:157], v[22:23], s[50:51], v[50:51] op_sel_hi:[1,0,0]
	v_pk_fma_f32 v[82:83], v[20:21], s[50:51], v[50:51] op_sel_hi:[1,0,0]
	v_pk_fma_f32 v[158:159], v[18:19], s[50:51], v[50:51] op_sel_hi:[1,0,0]
	v_pk_fma_f32 v[160:161], v[16:17], s[50:51], v[50:51] op_sel_hi:[1,0,0]
	v_lshlrev_b32_e32 v177, 4, v48
	s_addc_u32 s9, s31, 0
	v_mov_b64_e32 v[62:63], v[14:15]
	v_mov_b64_e32 v[30:31], v[14:15]
	v_mov_b64_e32 v[46:47], v[14:15]
	v_lshl_add_u64 v[142:143], s[6:7], 0, v[138:139]
	v_lshl_add_u64 v[144:145], s[34:35], 0, v[138:139]
	v_cmp_gt_u32_e64 s[6:7], 32, v169
	v_lshl_add_u32 v178, v167, 2, v171
	v_lshl_add_u64 v[146:147], s[8:9], 0, v[138:139]
	v_mov_b32_e32 v180, 0
	s_mov_b64 s[14:15], 0x89dc400
	v_mov_b64_e32 v[60:61], v[12:13]
	v_mov_b64_e32 v[58:59], v[10:11]
	v_mov_b64_e32 v[56:57], v[8:9]
	v_mov_b64_e32 v[54:55], v[6:7]
	v_mov_b64_e32 v[52:53], v[4:5]
	v_mov_b64_e32 v[50:51], v[2:3]
	v_mov_b64_e32 v[48:49], v[0:1]
	v_mov_b64_e32 v[28:29], v[12:13]
	v_mov_b64_e32 v[26:27], v[10:11]
	v_mov_b64_e32 v[24:25], v[8:9]
	v_mov_b64_e32 v[22:23], v[6:7]
	v_mov_b64_e32 v[20:21], v[4:5]
	v_mov_b64_e32 v[18:19], v[2:3]
	v_mov_b64_e32 v[16:17], v[0:1]
	v_mov_b64_e32 v[44:45], v[12:13]
	v_mov_b64_e32 v[42:43], v[10:11]
	v_mov_b64_e32 v[40:41], v[8:9]
	v_mov_b64_e32 v[38:39], v[6:7]
	v_mov_b64_e32 v[36:37], v[4:5]
	v_mov_b64_e32 v[34:35], v[2:3]
	v_mov_b64_e32 v[32:33], v[0:1]
	v_mov_b32_e32 v232, v112
	v_mov_b32_e32 v233, v112
	v_mov_b32_e32 v234, v112
	v_mov_b32_e32 v235, v112
	v_mov_b32_e32 v236, v112
	v_mov_b32_e32 v237, v112
	v_mov_b32_e32 v238, v112
	v_mov_b32_e32 v239, v112
	v_add_u32_e32 v176, v170, v176
	v_add_u32_e32 v176, 0x1000, v176
	v_add_u32_e32 v174, 0x2400, v173
	v_add_u32_e32 v175, 0x2400, v176
	ds_read_b128 v[204:207], v174
	ds_read_b64 v[208:209], v175
	ds_read_b128 v[216:219], v174 offset:512
	ds_read_b64 v[220:221], v175 offset:256
	s_lshl_b32 s78, s3, 4
	s_add_i32 s79, s78, 0x9000
	s_mul_i32 s80, s75, 0x186000
	s_add_u32 s80, s56, s80
	s_addc_u32 s81, s57, 0
	s_mov_b64 s[82:83], s[34:35]
	s_mul_i32 s84, s75, 0x208000
	s_add_u32 s84, s58, s84
	s_addc_u32 s85, s59, 0
	v_lshlrev_b32_e32 v231, 4, v169
	v_mov_b32_e32 v227, v181
	v_fmamk_f32 v230, v181, 0xbdd53b94, v164
	s_cmp_ge_u32 s3, 0x100
	s_cbranch_scc1 .Lprio_skip
	s_setprio 2
.Lprio_skip:
.LBB0_560:
	s_add_i32 s8, s53, -1
	s_cmpk_lg_i32 s53, 0x102
	s_cselect_b32 s17, s8, 0x100
	s_and_b32 s16, s8, 3
	s_add_i32 s18, s53, -3
	s_cmpk_lt_u32 s18, 0xfe
	s_cselect_b32 s86, s53, 0x100
	s_and_b32 s87, s53, 3
	s_add_i32 s19, s53, -2
	s_and_b32 s20, s19, 3
	s_cmp_lt_u32 s3, 0x100
	s_cbranch_scc1 .Ldma_done
	s_cmp_lt_u32 s3, 0x180
	s_cbranch_scc1 .Ldma_v
	s_cmp_ge_u32 s3, 0x1c0
	s_cselect_b32 s88, s86, s17
	s_cselect_b32 s89, s87, s16
	s_mul_i32 s89, s89, 0x2400
	s_mul_i32 s92, s88, 0x1800
	s_add_u32 s90, s80, s92
	s_addc_u32 s91, s81, 0
	s_mov_b32 m0, s89
	s_mul_i32 s92, s88, 0xc00
	global_load_lds_dwordx4 v231, s[90:91]
	global_load_lds_dwordx4 v231, s[90:91] offset:1024
	global_load_lds_dwordx4 v231, s[90:91] offset:2048
	global_load_lds_dwordx4 v231, s[90:91] offset:3072
	s_add_u32 s90, s90, 0x1000
	s_addc_u32 s91, s91, 0
	s_add_i32 s88, s89, 0x1000
	s_mov_b32 m0, s88
	s_add_i32 s89, s89, 0x1800
	global_load_lds_dwordx4 v231, s[90:91]
	global_load_lds_dwordx4 v231, s[90:91] offset:1024
	s_add_u32 s90, s82, s92
	s_addc_u32 s91, s83, 0
	s_mov_b32 m0, s89
	s_nop 0
	global_load_lds_dwordx4 v231, s[90:91]
	global_load_lds_dwordx4 v231, s[90:91] offset:1024
	global_load_lds_dwordx4 v231, s[90:91] offset:2048
	s_branch .Ldma_done
.Ldma_v:
	s_cmp_ge_u32 s3, 0x140
	s_cselect_b32 s88, s17, s19
	s_cselect_b32 s89, s16, s20
	s_lshl_b32 s88, s88, 13
	s_add_u32 s90, s84, s88
	s_addc_u32 s91, s85, 0
	s_lshl_b32 s89, s89, 13
	s_add_i32 s89, s89, 0x9000
	s_mov_b32 m0, s89
	s_add_i32 s89, s89, 0x1000
	global_load_lds_dwordx4 v231, s[90:91]
	global_load_lds_dwordx4 v231, s[90:91] offset:1024
	global_load_lds_dwordx4 v231, s[90:91] offset:2048
	global_load_lds_dwordx4 v231, s[90:91] offset:3072
	s_add_u32 s90, s90, 0x1000
	s_addc_u32 s91, s91, 0
	s_mov_b32 m0, s89
	s_nop 0
	global_load_lds_dwordx4 v231, s[90:91]
	global_load_lds_dwordx4 v231, s[90:91] offset:1024
	global_load_lds_dwordx4 v231, s[90:91] offset:2048
	global_load_lds_dwordx4 v231, s[90:91] offset:3072
